# scan loop stage 2: LDS read bases precomputed, lgkmcnt waits merged per MFMA group, hazard pads restored
# speedup vs baseline: 1.0005x; 1.0005x over previous
.LBB0_1850:
	s_and_b64 vcc, exec, s[4:5]
	s_cbranch_vccz .LBB0_1853
	s_add_u32 s14, s0, 0x15a00000
	s_addc_u32 s15, s1, 0
	s_lshl_b32 s5, s10, 5
	s_lshl_b32 s4, s11, 4
	s_and_b32 s5, s5, 0x60
	s_add_i32 s16, s4, s5
	s_waitcnt vmcnt(18)
	v_and_b32_e32 v7, 15, v100
	s_ashr_i32 s9, s8, 31
	s_lshl_b64 s[4:5], s[8:9], 22
	v_or_b32_e32 v0, s16, v7
	s_add_u32 s4, s14, s4
	v_ashrrev_i32_e32 v1, 31, v0
	s_addc_u32 s5, s15, s5
	v_lshlrev_b64 v[0:1], 7, v[0:1]
	v_lshrrev_b32_e32 v6, 4, v101
	v_lshl_add_u64 v[2:3], s[4:5], 0, v[0:1]
	s_lshl_b64 s[4:5], s[8:9], 8
	s_lshl_b64 s[10:11], s[8:9], 10
	v_lshlrev_b32_e32 v160, 3, v6
	s_add_u32 s18, s0, s10
	v_lshl_add_u64 v[2:3], v[2:3], 0, v[160:161]
	s_addc_u32 s19, s1, s11
	s_mov_b64 s[10:11], 0x4000
	s_movk_i32 s3, 0x4000
	global_load_dwordx2 v[36:37], v[2:3], off
	global_load_dwordx2 v[38:39], v[2:3], off offset:32
	global_load_dwordx2 v[34:35], v[2:3], off offset:64
	global_load_dwordx2 v[32:33], v[2:3], off offset:96
	v_lshl_add_u64 v[4:5], v[2:3], 0, s[10:11]
	v_add_co_u32_e32 v2, vcc, s3, v2
	v_lshl_add_u64 v[0:1], s[14:15], 0, v[0:1]
	s_nop 0
	v_addc_co_u32_e32 v3, vcc, 0, v3, vcc
	global_load_dwordx2 v[76:77], v[2:3], off
	global_load_dwordx2 v[72:73], v[4:5], off offset:32
	global_load_dwordx2 v[74:75], v[4:5], off offset:64
	global_load_dwordx2 v[68:69], v[4:5], off offset:96
	global_load_dwordx2 v[78:79], v211, s[18:19]
	s_waitcnt vmcnt(14)
	v_lshl_add_u64 v[56:57], v[0:1], 0, v[160:161]
	v_lshlrev_b32_e32 v0, 8, v7
	v_bitop3_b32 v1, v6, v100, 15 bitop3:0x78
	s_waitcnt vmcnt(11)
	v_lshl_or_b32 v71, v1, 4, v0
	v_bitop3_b32 v1, v6, v7, 4 bitop3:0x36
	v_lshl_or_b32 v83, v1, 4, v0
	v_bitop3_b32 v1, v6, v7, 8 bitop3:0x36
	v_lshl_or_b32 v87, v1, 4, v0
	v_bitop3_b32 v1, v6, v7, 12 bitop3:0x36
	s_add_u32 s12, s18, 0x17200000
	v_lshl_or_b32 v91, v1, 4, v0
	v_and_b32_e32 v0, 7, v100
	s_addc_u32 s13, s19, 0
	s_lshl_b32 s8, s8, 7
	v_bitop3_b32 v1, v6, v100, 7 bitop3:0x78
	v_bitop3_b32 v0, v6, v0, 4 bitop3:0x36
	s_ashr_i32 s9, s8, 31
	s_ashr_i32 s17, s16, 31
	v_lshlrev_b32_e32 v1, 4, v1
	v_lshlrev_b32_e32 v0, 4, v0
	s_add_i32 s10, 0, 0x16000
	v_mul_u32_u24_e32 v5, 0x3800, v6
	v_add_u32_e32 v6, s10, v1
	v_add_u32_e32 v8, s10, v0
	s_add_i32 s10, 0, 0x1a000
	s_lshl_b64 s[8:9], s[8:9], 1
	s_lshl_b64 s[14:15], s[16:17], 1
	s_add_u32 s8, s8, s14
	s_addc_u32 s9, s9, s15
	v_lshlrev_b32_e32 v160, 1, v5
	v_add_u32_e32 v3, 0, v1
	v_add_u32_e32 v4, 0, v0
	v_add_u32_e32 v9, s10, v1
	v_add_u32_e32 v10, s10, v0
	v_lshl_add_u64 v[0:1], s[8:9], 0, v[160:161]
	v_lshl_or_b32 v0, v7, 1, v0
	v_lshlrev_b32_e32 v2, 7, v7
	v_lshl_add_u64 v[0:1], s[0:1], 0, v[0:1]
	s_mov_b64 s[0:1], 0x9600000
	v_mov_b32_e32 v16, 0
	s_mov_b32 s11, 0
	v_or_b32_e32 v80, 0x1000, v71
	v_or_b32_e32 v81, 0x2000, v71
	v_or_b32_e32 v82, 0x3000, v71
	v_or_b32_e32 v84, 0x1000, v83
	v_or_b32_e32 v85, 0x2000, v83
	v_or_b32_e32 v86, 0x3000, v83
	v_or_b32_e32 v88, 0x1000, v87
	v_or_b32_e32 v89, 0x2000, v87
	v_or_b32_e32 v90, 0x3000, v87
	v_or_b32_e32 v92, 0x1000, v91
	v_or_b32_e32 v93, 0x2000, v91
	v_or_b32_e32 v94, 0x3000, v91
	v_lshl_add_u64 v[58:59], v[0:1], 0, s[0:1]
	v_add_u32_e32 v95, v3, v2
	v_add_u32_e32 v96, v4, v2
	v_add_u32_e32 v97, v6, v2
	v_add_u32_e32 v98, v8, v2
	v_add_u32_e32 v99, v9, v2
	v_add_u32_e32 v100, v10, v2
	v_mov_b32_e32 v17, v16
	v_mov_b32_e32 v18, v16
	v_mov_b32_e32 v19, v16
	v_mov_b32_e32 v8, v16
	v_mov_b32_e32 v9, v16
	v_mov_b32_e32 v10, v16
	v_mov_b32_e32 v11, v16
	v_mov_b32_e32 v20, v16
	v_mov_b32_e32 v21, v16
	v_mov_b32_e32 v22, v16
	v_mov_b32_e32 v23, v16
	v_mov_b32_e32 v0, v16
	v_mov_b32_e32 v1, v16
	v_mov_b32_e32 v2, v16
	v_mov_b32_e32 v3, v16
	v_mov_b32_e32 v24, v16
	v_mov_b32_e32 v25, v16
	v_mov_b32_e32 v26, v16
	v_mov_b32_e32 v27, v16
	v_mov_b32_e32 v12, v16
	v_mov_b32_e32 v13, v16
	v_mov_b32_e32 v14, v16
	v_mov_b32_e32 v15, v16
	v_mov_b32_e32 v28, v16
	v_mov_b32_e32 v29, v16
	v_mov_b32_e32 v30, v16
	v_mov_b32_e32 v31, v16
	v_mov_b32_e32 v4, v16
	v_mov_b32_e32 v5, v16
	v_mov_b32_e32 v6, v16
	v_mov_b32_e32 v7, v16
	v_add_u32_e32 v206, 0x12000, v71
	v_add_u32_e32 v207, 0x12000, v83
	v_add_u32_e32 v249, 0x12000, v87
	v_add_u32_e32 v250, 0x12000, v91
	v_readfirstlane_b32 s16, v58
	v_readfirstlane_b32 s17, v59
	s_nop 1
	v_subrev_u32_e32 v202, s16, v58
	v_mov_b32_e32 v222, v202
	v_add_u32_e32 v223, 0x1c00, v202
	v_add_u32_e32 v224, 0x3800, v202
	v_add_u32_e32 v225, 0x5400, v202
	v_add_u32_e32 v226, 0x1c000, v202
	v_add_u32_e32 v227, 0x1dc00, v202
	v_add_u32_e32 v228, 0x1f800, v202
	v_add_u32_e32 v229, 0x21400, v202
	v_add_u32_e32 v230, 0x38000, v202
	v_add_u32_e32 v231, 0x39c00, v202
	v_add_u32_e32 v232, 0x3b800, v202
	v_add_u32_e32 v233, 0x3d400, v202
	v_add_u32_e32 v234, 0x54000, v202
	v_add_u32_e32 v235, 0x55c00, v202
	v_add_u32_e32 v236, 0x57800, v202
	v_add_u32_e32 v237, 0x59400, v202
	s_sub_u32 s18, s16, 0x70000
	s_subb_u32 s19, s17, 0
	s_sub_u32 s16, s16, 0xe0000
	s_subb_u32 s17, s17, 0
	s_waitcnt vmcnt(0)
	v_mov_b32_e32 v70, v79
	s_waitcnt lgkmcnt(0)
	s_barrier
.LBB0_1852:
	s_add_u32 s16, s16, 0xe0000
	s_addc_u32 s17, s17, 0
	s_add_u32 s18, s18, 0xe0000
	s_addc_u32 s19, s19, 0
	s_add_i32 s8, s11, 2
	s_cmpk_lt_u32 s11, 0xfe
	s_cselect_b32 s66, s8, 0xff
	s_add_u32 s0, s4, s66
	s_addc_u32 s1, s5, 0
	s_lshl_b64 s[0:1], s[0:1], 14
	s_lshl_b64 s[14:15], s[66:67], 2
	s_add_u32 s14, s12, s14
	v_lshl_add_u64 v[40:41], v[56:57], 0, s[0:1]
	s_addc_u32 s15, s13, s15
	global_load_dwordx2 v[66:67], v[40:41], off
	global_load_dwordx2 v[60:61], v[40:41], off offset:32
	global_load_dwordx2 v[62:63], v[40:41], off offset:64
	global_load_dwordx2 v[64:65], v[40:41], off offset:96
	global_load_dword v79, v161, s[14:15]
	ds_read_b128 v[114:117], v71
	ds_read_b128 v[118:121], v71 offset:4096
	ds_read_b128 v[122:125], v71 offset:16384
	ds_read_b128 v[126:129], v71 offset:20480
	ds_read_b128 v[130:133], v71 offset:8192
	ds_read_b128 v[134:137], v71 offset:12288
	ds_read_b128 v[138:141], v71 offset:24576
	ds_read_b128 v[142:145], v71 offset:28672
	s_min_u32 s0, s11, 0xfc
	s_add_i32 s9, s0, 3
	s_add_u32 s0, s4, s9
	s_addc_u32 s1, s5, 0
	s_lshl_b64 s[0:1], s[0:1], 14
	s_lshl_b32 s10, s9, 2
	s_add_i32 s9, 0, 0x12000
	v_lshl_add_u64 v[202:203], v[56:57], 0, s[0:1]
	v_mov_b32_e32 v204, s10
	global_load_dwordx2 v[238:239], v[202:203], off
	global_load_dwordx2 v[240:241], v[202:203], off offset:32
	global_load_dwordx2 v[242:243], v[202:203], off offset:64
	global_load_dwordx2 v[244:245], v[202:203], off offset:96
	global_load_dword v205, v204, s[12:13]
	v_lshlrev_b32_e32 v106, 16, v36
	v_and_b32_e32 v107, 0xffff0000, v36
	v_lshlrev_b32_e32 v108, 16, v37
	v_and_b32_e32 v109, 0xffff0000, v37
	v_lshlrev_b32_e32 v36, 16, v38
	v_and_b32_e32 v37, 0xffff0000, v38
	v_lshlrev_b32_e32 v38, 16, v39
	v_and_b32_e32 v39, 0xffff0000, v39
	s_cmpk_gt_u32 s11, 0xfd
	v_cvt_pk_bf16_f32 v40, v16, v17
	v_cvt_pk_bf16_f32 v41, v18, v19
	v_cvt_pk_bf16_f32 v42, v8, v9
	v_cvt_pk_bf16_f32 v43, v10, v11
	v_cvt_pk_bf16_f32 v44, v20, v21
	v_cvt_pk_bf16_f32 v45, v22, v23
	v_cvt_pk_bf16_f32 v46, v0, v1
	v_cvt_pk_bf16_f32 v47, v2, v3
	v_cvt_pk_bf16_f32 v48, v24, v25
	v_cvt_pk_bf16_f32 v49, v26, v27
	v_cvt_pk_bf16_f32 v50, v12, v13
	v_cvt_pk_bf16_f32 v51, v14, v15
	v_cvt_pk_bf16_f32 v52, v28, v29
	v_cvt_pk_bf16_f32 v53, v30, v31
	v_cvt_pk_bf16_f32 v54, v4, v5
	v_cvt_pk_bf16_f32 v55, v6, v7
	v_lshlrev_b32_e32 v110, 16, v34
	v_and_b32_e32 v111, 0xffff0000, v34
	v_lshlrev_b32_e32 v112, 16, v35
	v_and_b32_e32 v113, 0xffff0000, v35
	v_lshlrev_b32_e32 v146, 16, v32
	v_and_b32_e32 v147, 0xffff0000, v32
	v_lshlrev_b32_e32 v148, 16, v33
	v_and_b32_e32 v149, 0xffff0000, v33
	ds_read_b128 v[32:35], v83
	ds_read_b128 v[150:153], v83 offset:4096
	ds_read_b128 v[154:157], v83 offset:16384
	ds_read_b128 v[166:169], v83 offset:20480
	ds_read_b128 v[170:173], v83 offset:8192
	ds_read_b128 v[174:177], v83 offset:12288
	ds_read_b128 v[178:181], v83 offset:24576
	ds_read_b128 v[182:185], v83 offset:28672
	s_waitcnt lgkmcnt(8)
	v_mfma_f32_16x16x32_bf16 v[36:39], v[118:121], v[40:43], v[36:39]
	v_mfma_f32_16x16x32_bf16 v[106:109], v[114:117], v[40:43], v[106:109]
	v_mfma_f32_16x16x32_bf16 v[114:117], v[122:125], v[40:43], 0
	v_mfma_f32_16x16x32_bf16 v[118:121], v[126:129], v[40:43], 0
	v_mfma_f32_16x16x32_bf16 v[110:113], v[130:133], v[40:43], v[110:113]
	v_mfma_f32_16x16x32_bf16 v[122:125], v[138:141], v[40:43], 0
	v_mfma_f32_16x16x32_bf16 v[126:129], v[134:137], v[40:43], v[146:149]
	v_mfma_f32_16x16x32_bf16 v[40:43], v[142:145], v[40:43], 0
	ds_read_b128 v[130:133], v87
	ds_read_b128 v[134:137], v87 offset:4096
	ds_read_b128 v[138:141], v87 offset:16384
	ds_read_b128 v[142:145], v87 offset:20480
	ds_read_b128 v[146:149], v87 offset:8192
	ds_read_b128 v[186:189], v87 offset:12288
	ds_read_b128 v[190:193], v87 offset:24576
	ds_read_b128 v[194:197], v87 offset:28672
	s_waitcnt lgkmcnt(8)
	v_mfma_f32_16x16x32_bf16 v[32:35], v[32:35], v[44:47], v[106:109]
	v_mfma_f32_16x16x32_bf16 v[36:39], v[150:153], v[44:47], v[36:39]
	v_mfma_f32_16x16x32_bf16 v[106:109], v[154:157], v[44:47], v[114:117]
	v_mfma_f32_16x16x32_bf16 v[114:117], v[166:169], v[44:47], v[118:121]
	v_mfma_f32_16x16x32_bf16 v[110:113], v[170:173], v[44:47], v[110:113]
	v_mfma_f32_16x16x32_bf16 v[118:121], v[178:181], v[44:47], v[122:125]
	v_mfma_f32_16x16x32_bf16 v[122:125], v[174:177], v[44:47], v[126:129]
	v_mfma_f32_16x16x32_bf16 v[40:43], v[182:185], v[44:47], v[40:43]
	s_nop 1
	ds_read_b128 v[126:129], v91
	ds_read_b128 v[150:153], v91 offset:4096
	ds_read_b128 v[154:157], v91 offset:16384
	ds_read_b128 v[166:169], v91 offset:20480
	ds_read_b128 v[170:173], v91 offset:8192
	ds_read_b128 v[174:177], v91 offset:12288
	ds_read_b128 v[178:181], v91 offset:24576
	ds_read_b128 v[182:185], v91 offset:28672
	s_waitcnt lgkmcnt(8)
	v_mfma_f32_16x16x32_bf16 v[130:133], v[130:133], v[48:51], v[32:35]
	v_mfma_f32_16x16x32_bf16 v[106:109], v[138:141], v[48:51], v[106:109]
	v_mfma_f32_16x16x32_bf16 v[134:137], v[134:137], v[48:51], v[36:39]
	v_mfma_f32_16x16x32_bf16 v[114:117], v[142:145], v[48:51], v[114:117]
	v_mfma_f32_16x16x32_bf16 v[110:113], v[146:149], v[48:51], v[110:113]
	v_mfma_f32_16x16x32_bf16 v[118:121], v[190:193], v[48:51], v[118:121]
	v_mfma_f32_16x16x32_bf16 v[122:125], v[186:189], v[48:51], v[122:125]
	v_mfma_f32_16x16x32_bf16 v[48:51], v[194:197], v[48:51], v[40:43]
	ds_read_b128 v[138:141], v95 offset:32768
	ds_read_b128 v[44:47], v95 offset:34816
	ds_read_b128 v[142:145], v96 offset:32768
	ds_read_b128 v[40:43], v96 offset:34816
	ds_read_b128 v[146:149], v95 offset:36864
	ds_read_b128 v[36:39], v95 offset:38912
	ds_read_b128 v[186:189], v96 offset:36864
	ds_read_b128 v[32:35], v96 offset:38912
	s_waitcnt lgkmcnt(8)
	v_mfma_f32_16x16x32_bf16 v[126:129], v[126:129], v[52:55], v[130:133]
	v_mfma_f32_16x16x32_bf16 v[106:109], v[154:157], v[52:55], v[106:109]
	v_mfma_f32_16x16x32_bf16 v[130:133], v[150:153], v[52:55], v[134:137]
	v_mfma_f32_16x16x32_bf16 v[114:117], v[166:169], v[52:55], v[114:117]
	v_mfma_f32_16x16x32_bf16 v[110:113], v[170:173], v[52:55], v[110:113]
	v_mfma_f32_16x16x32_bf16 v[118:121], v[178:181], v[52:55], v[118:121]
	v_mfma_f32_16x16x32_bf16 v[122:125], v[174:177], v[52:55], v[122:125]
	v_mfma_f32_16x16x32_bf16 v[134:137], v[182:185], v[52:55], v[48:51]
	ds_read_b128 v[154:157], v95 offset:40960
	ds_read_b128 v[166:169], v96 offset:40960
	ds_read_b128 v[170:173], v95 offset:43008
	ds_read_b128 v[174:177], v96 offset:43008
	ds_read_b128 v[178:181], v95 offset:45056
	ds_read_b128 v[182:185], v96 offset:45056
	ds_read_b128 v[48:51], v95 offset:47104
	ds_read_b128 v[52:55], v96 offset:47104
	v_pk_mul_f32 v[18:19], v[78:79], v[18:19] op_sel_hi:[0,1]
	v_pk_mul_f32 v[16:17], v[78:79], v[16:17] op_sel_hi:[0,1]
	v_pk_mul_f32 v[22:23], v[78:79], v[22:23] op_sel_hi:[0,1]
	v_pk_mul_f32 v[20:21], v[78:79], v[20:21] op_sel_hi:[0,1]
	v_pk_mul_f32 v[26:27], v[78:79], v[26:27] op_sel_hi:[0,1]
	v_pk_mul_f32 v[24:25], v[78:79], v[24:25] op_sel_hi:[0,1]
	v_pk_mul_f32 v[152:153], v[78:79], v[30:31] op_sel_hi:[0,1]
	v_pk_mul_f32 v[150:151], v[78:79], v[28:29] op_sel_hi:[0,1]
	v_cvt_pk_bf16_f32 v126, v126, v127
	v_cvt_pk_bf16_f32 v127, v128, v129
	v_cvt_pk_bf16_f32 v128, v130, v131
	v_cvt_pk_bf16_f32 v129, v132, v133
	v_cvt_pk_bf16_f32 v110, v110, v111
	v_cvt_pk_bf16_f32 v111, v112, v113
	s_waitcnt lgkmcnt(14)
	v_mfma_f32_16x16x32_bf16 v[16:19], v[138:141], v[126:129], v[16:19]
	v_cvt_pk_bf16_f32 v112, v122, v123
	v_cvt_pk_bf16_f32 v113, v124, v125
	s_waitcnt lgkmcnt(9)
	v_mfma_f32_16x16x32_bf16 v[20:23], v[146:149], v[126:129], v[20:23]
	v_mfma_f32_16x16x32_bf16 v[28:31], v[142:145], v[110:113], v[16:19]
	v_mfma_f32_16x16x32_bf16 v[20:23], v[186:189], v[110:113], v[20:23]
	ds_read_b128 v[122:125], v95 offset:49152
	ds_read_b128 v[130:133], v95 offset:51200
	ds_read_b128 v[138:141], v96 offset:49152
	ds_read_b128 v[142:145], v96 offset:51200
	ds_read_b128 v[146:149], v95 offset:53248
	ds_read_b128 v[186:189], v95 offset:55296
	ds_read_b128 v[190:193], v96 offset:53248
	ds_read_b128 v[194:197], v96 offset:55296
	s_waitcnt lgkmcnt(10)
	v_mfma_f32_16x16x32_bf16 v[16:19], v[154:157], v[126:129], v[24:27]
	v_mfma_f32_16x16x32_bf16 v[150:153], v[178:181], v[126:129], v[150:153]
	v_mfma_f32_16x16x32_bf16 v[24:27], v[166:169], v[110:113], v[16:19]
	v_mfma_f32_16x16x32_bf16 v[16:19], v[182:185], v[110:113], v[150:153]
	s_waitcnt lgkmcnt(7)
	v_mfma_f32_16x16x32_bf16 v[106:109], v[122:125], v[126:129], v[106:109]
	v_pk_mul_f32 v[10:11], v[78:79], v[10:11] op_sel_hi:[0,1]
	v_pk_mul_f32 v[8:9], v[78:79], v[8:9] op_sel_hi:[0,1]
	s_waitcnt lgkmcnt(5)
	v_mfma_f32_16x16x32_bf16 v[106:109], v[138:141], v[110:113], v[106:109]
	v_mul_f32_e64 v2, v78, v2
	v_mul_f32_e64 v3, v78, v3
	v_pk_mul_f32 v[0:1], v[78:79], v[0:1] op_sel_hi:[0,1]
	v_pk_mul_f32 v[6:7], v[78:79], v[6:7] op_sel_hi:[0,1]
	v_mfma_f32_16x16x32_bf16 v[114:117], v[130:133], v[126:129], v[114:117]
	v_mul_f32_e64 v4, v78, v4
	v_mul_f32_e64 v5, v78, v5
	s_nop 0
	v_cvt_pk_bf16_f32 v105, v106, s0
	s_waitcnt lgkmcnt(3)
	v_mfma_f32_16x16x32_bf16 v[118:121], v[146:149], v[126:129], v[118:121]
	global_store_short v222, v105, s[16:17]
	v_cvt_pk_bf16_f32 v105, v107, s0
	s_waitcnt lgkmcnt(2)
	v_mfma_f32_16x16x32_bf16 v[122:125], v[186:189], v[126:129], v[134:137]
	global_store_short v223, v105, s[16:17]
	v_cvt_pk_bf16_f32 v105, v108, s0
	v_mfma_f32_16x16x32_bf16 v[114:117], v[142:145], v[110:113], v[114:117]
	global_store_short v224, v105, s[16:17]
	v_cvt_pk_bf16_f32 v105, v109, s0
	v_lshlrev_b32_e32 v150, 16, v68
	s_waitcnt lgkmcnt(1)
	v_mfma_f32_16x16x32_bf16 v[106:109], v[190:193], v[110:113], v[118:121]
	v_and_b32_e32 v151, 0xffff0000, v68
	v_lshlrev_b32_e32 v152, 16, v69
	v_and_b32_e32 v153, 0xffff0000, v69
	global_store_short v225, v105, s[16:17]
	s_waitcnt lgkmcnt(0)
	v_mfma_f32_16x16x32_bf16 v[118:121], v[194:197], v[110:113], v[122:125]
	v_cvt_pk_bf16_f32 v105, v114, s0
	global_store_short v226, v105, s[16:17]
	v_cvt_pk_bf16_f32 v105, v115, s0
	global_store_short v227, v105, s[16:17]
	v_cvt_pk_bf16_f32 v105, v116, s0
	global_store_short v228, v105, s[16:17]
	v_cvt_pk_bf16_f32 v105, v117, s0
	global_store_short v229, v105, s[16:17]
	v_cvt_pk_bf16_f32 v105, v106, s0
	global_store_short v230, v105, s[16:17]
	v_cvt_pk_bf16_f32 v105, v107, s0
	global_store_short v231, v105, s[16:17]
	v_cvt_pk_bf16_f32 v105, v108, s0
	global_store_short v232, v105, s[16:17]
	v_cvt_pk_bf16_f32 v105, v109, s0
	global_store_short v233, v105, s[16:17]
	v_cvt_pk_bf16_f32 v105, v118, s0
	global_store_short v234, v105, s[16:17]
	v_mfma_f32_16x16x32_bf16 v[8:11], v[44:47], v[126:129], v[8:11]
	v_cvt_pk_bf16_f32 v105, v119, s0
	global_store_short v235, v105, s[16:17]
	v_cvt_pk_bf16_f32 v105, v120, s0
	v_mfma_f32_16x16x32_bf16 v[40:43], v[40:43], v[110:113], v[8:11]
	global_store_short v236, v105, s[16:17]
	v_cvt_pk_bf16_f32 v44, v121, s0
	v_lshlrev_b32_e32 v114, 16, v72
	s_nop 0
	v_pk_mul_f32 v[8:9], v[78:79], v[12:13] op_sel_hi:[0,1]
	v_mfma_f32_16x16x32_bf16 v[0:3], v[36:39], v[126:129], v[0:3]
	global_store_short v237, v44, s[16:17]
	s_barrier
	v_mfma_f32_16x16x32_bf16 v[4:7], v[48:51], v[126:129], v[4:7]
	v_pk_mul_f32 v[10:11], v[78:79], v[14:15] op_sel_hi:[0,1]
	v_mfma_f32_16x16x32_bf16 v[4:7], v[52:55], v[110:113], v[4:7]
	ds_read_b128 v[118:121], v71 offset:57344
	ds_read_b128 v[122:125], v71 offset:61440
	v_cvt_pk_bf16_f32 v12, v28, v29
	v_mfma_f32_16x16x32_bf16 v[8:11], v[170:173], v[126:129], v[8:11]
	ds_read_b128 v[126:129], v206
	ds_read_b128 v[130:133], v206 offset:4096
	ds_read_b128 v[134:137], v81 offset:57344
	ds_read_b128 v[138:141], v206 offset:8192
	v_mfma_f32_16x16x32_bf16 v[0:3], v[32:35], v[110:113], v[0:3]
	ds_read_b128 v[142:145], v82 offset:57344
	ds_read_b128 v[146:149], v206 offset:12288
	v_cvt_pk_bf16_f32 v13, v30, v31
	v_mfma_f32_16x16x32_bf16 v[8:11], v[174:177], v[110:113], v[8:11]
	v_cvt_pk_bf16_f32 v14, v40, v41
	v_cvt_pk_bf16_f32 v15, v42, v43
	v_cvt_pk_bf16_f32 v32, v20, v21
	v_cvt_pk_bf16_f32 v33, v22, v23
	v_cvt_pk_bf16_f32 v34, v0, v1
	v_cvt_pk_bf16_f32 v35, v2, v3
	v_and_b32_e32 v115, 0xffff0000, v72
	v_lshlrev_b32_e32 v116, 16, v73
	v_and_b32_e32 v117, 0xffff0000, v73
	v_lshlrev_b32_e32 v72, 16, v74
	v_and_b32_e32 v73, 0xffff0000, v74
	v_lshlrev_b32_e32 v74, 16, v75
	v_and_b32_e32 v75, 0xffff0000, v75
	v_cvt_pk_bf16_f32 v50, v24, v25
	v_cvt_pk_bf16_f32 v51, v26, v27
	v_cvt_pk_bf16_f32 v52, v8, v9
	v_cvt_pk_bf16_f32 v53, v10, v11
	v_cvt_pk_bf16_f32 v106, v16, v17
	v_cvt_pk_bf16_f32 v107, v18, v19
	v_cvt_pk_bf16_f32 v108, v4, v5
	v_cvt_pk_bf16_f32 v109, v6, v7
	v_lshlrev_b32_e32 v110, 16, v76
	v_and_b32_e32 v111, 0xffff0000, v76
	v_lshlrev_b32_e32 v112, 16, v77
	v_and_b32_e32 v113, 0xffff0000, v77
	ds_read_b128 v[154:157], v83 offset:57344
	ds_read_b128 v[166:169], v83 offset:61440
	ds_read_b128 v[170:173], v207
	ds_read_b128 v[174:177], v207 offset:4096
	ds_read_b128 v[178:181], v85 offset:57344
	ds_read_b128 v[182:185], v207 offset:8192
	ds_read_b128 v[186:189], v86 offset:57344
	ds_read_b128 v[190:193], v207 offset:12288
	s_waitcnt lgkmcnt(8)
	v_mfma_f32_16x16x32_bf16 v[110:113], v[118:121], v[12:15], v[110:113]
	v_mfma_f32_16x16x32_bf16 v[118:121], v[126:129], v[12:15], 0
	v_mfma_f32_16x16x32_bf16 v[114:117], v[122:125], v[12:15], v[114:117]
	v_mfma_f32_16x16x32_bf16 v[122:125], v[130:133], v[12:15], 0
	v_mfma_f32_16x16x32_bf16 v[72:75], v[134:137], v[12:15], v[72:75]
	v_mfma_f32_16x16x32_bf16 v[126:129], v[138:141], v[12:15], 0
	v_mfma_f32_16x16x32_bf16 v[130:133], v[142:145], v[12:15], v[150:153]
	v_mfma_f32_16x16x32_bf16 v[12:15], v[146:149], v[12:15], 0
	ds_read_b128 v[134:137], v87 offset:57344
	ds_read_b128 v[102:105], v87 offset:61440
	ds_read_b128 v[138:141], v249
	ds_read_b128 v[142:145], v249 offset:4096
	ds_read_b128 v[146:149], v89 offset:57344
	ds_read_b128 v[150:153], v249 offset:8192
	ds_read_b128 v[194:197], v90 offset:57344
	ds_read_b128 v[198:201], v249 offset:12288
	s_waitcnt lgkmcnt(8)
	v_mfma_f32_16x16x32_bf16 v[72:75], v[178:181], v[32:35], v[72:75]
	v_mfma_f32_16x16x32_bf16 v[12:15], v[190:193], v[32:35], v[12:15]
	v_mfma_f32_16x16x32_bf16 v[110:113], v[154:157], v[32:35], v[110:113]
	v_mfma_f32_16x16x32_bf16 v[118:121], v[170:173], v[32:35], v[118:121]
	v_mfma_f32_16x16x32_bf16 v[114:117], v[166:169], v[32:35], v[114:117]
	v_mfma_f32_16x16x32_bf16 v[122:125], v[174:177], v[32:35], v[122:125]
	v_mfma_f32_16x16x32_bf16 v[126:129], v[182:185], v[32:35], v[126:129]
	v_mfma_f32_16x16x32_bf16 v[130:133], v[186:189], v[32:35], v[130:133]
	ds_read_b128 v[32:35], v91 offset:57344
	ds_read_b128 v[154:157], v91 offset:61440
	ds_read_b128 v[166:169], v250
	ds_read_b128 v[170:173], v250 offset:4096
	ds_read_b128 v[174:177], v93 offset:57344
	ds_read_b128 v[178:181], v250 offset:8192
	ds_read_b128 v[182:185], v94 offset:57344
	ds_read_b128 v[186:189], v250 offset:12288
	s_waitcnt lgkmcnt(8)
	v_mfma_f32_16x16x32_bf16 v[72:75], v[146:149], v[50:53], v[72:75]
	v_mfma_f32_16x16x32_bf16 v[12:15], v[198:201], v[50:53], v[12:15]
	v_mfma_f32_16x16x32_bf16 v[110:113], v[134:137], v[50:53], v[110:113]
	v_mfma_f32_16x16x32_bf16 v[118:121], v[138:141], v[50:53], v[118:121]
	v_mfma_f32_16x16x32_bf16 v[102:105], v[102:105], v[50:53], v[114:117]
	v_mfma_f32_16x16x32_bf16 v[114:117], v[142:145], v[50:53], v[122:125]
	v_mfma_f32_16x16x32_bf16 v[122:125], v[150:153], v[50:53], v[126:129]
	v_mfma_f32_16x16x32_bf16 v[126:129], v[194:197], v[50:53], v[130:133]
	ds_read_b128 v[50:53], v97
	s_nop 1
	ds_read_b128 v[130:133], v97 offset:2048
	ds_read_b128 v[134:137], v98
	ds_read_b128 v[138:141], v98 offset:2048
	ds_read_b128 v[142:145], v97 offset:4096
	ds_read_b128 v[146:149], v97 offset:6144
	ds_read_b128 v[150:153], v98 offset:4096
	ds_read_b128 v[190:193], v98 offset:6144
	s_waitcnt lgkmcnt(8)
	v_mfma_f32_16x16x32_bf16 v[32:35], v[32:35], v[106:109], v[110:113]
	v_mfma_f32_16x16x32_bf16 v[72:75], v[174:177], v[106:109], v[72:75]
	v_mfma_f32_16x16x32_bf16 v[110:113], v[166:169], v[106:109], v[118:121]
	v_mfma_f32_16x16x32_bf16 v[102:105], v[154:157], v[106:109], v[102:105]
	v_mfma_f32_16x16x32_bf16 v[114:117], v[170:173], v[106:109], v[114:117]
	v_mfma_f32_16x16x32_bf16 v[118:121], v[178:181], v[106:109], v[122:125]
	v_mfma_f32_16x16x32_bf16 v[122:125], v[182:185], v[106:109], v[126:129]
	v_mfma_f32_16x16x32_bf16 v[106:109], v[186:189], v[106:109], v[12:15]
	ds_read_b128 v[154:157], v97 offset:8192
	ds_read_b128 v[166:169], v98 offset:8192
	ds_read_b128 v[170:173], v97 offset:10240
	ds_read_b128 v[174:177], v98 offset:10240
	ds_read_b128 v[178:181], v97 offset:12288
	ds_read_b128 v[182:185], v98 offset:12288
	ds_read_b128 v[186:189], v97 offset:14336
	ds_read_b128 v[194:197], v98 offset:14336
	v_pk_mul_f32 v[14:15], v[70:71], v[30:31] op_sel_hi:[0,1]
	v_pk_mul_f32 v[12:13], v[70:71], v[28:29] op_sel_hi:[0,1]
	v_pk_mul_f32 v[30:31], v[70:71], v[42:43] op_sel_hi:[0,1]
	v_pk_mul_f32 v[28:29], v[70:71], v[40:41] op_sel_hi:[0,1]
	v_pk_mul_f32 v[22:23], v[70:71], v[22:23] op_sel_hi:[0,1]
	v_pk_mul_f32 v[20:21], v[70:71], v[20:21] op_sel_hi:[0,1]
	v_pk_mul_f32 v[2:3], v[70:71], v[2:3] op_sel_hi:[0,1]
	v_pk_mul_f32 v[0:1], v[70:71], v[0:1] op_sel_hi:[0,1]
	v_pk_mul_f32 v[26:27], v[70:71], v[26:27] op_sel_hi:[0,1]
	v_pk_mul_f32 v[24:25], v[70:71], v[24:25] op_sel_hi:[0,1]
	v_pk_mul_f32 v[6:7], v[70:71], v[6:7] op_sel_hi:[0,1]
	v_pk_mul_f32 v[4:5], v[70:71], v[4:5] op_sel_hi:[0,1]
	v_pk_mul_f32 v[42:43], v[70:71], v[10:11] op_sel_hi:[0,1]
	v_pk_mul_f32 v[40:41], v[70:71], v[8:9] op_sel_hi:[0,1]
	v_pk_mul_f32 v[128:129], v[70:71], v[18:19] op_sel_hi:[0,1]
	v_pk_mul_f32 v[126:127], v[70:71], v[16:17] op_sel_hi:[0,1]
	v_cvt_pk_bf16_f32 v32, v32, v33
	v_cvt_pk_bf16_f32 v33, v34, v35
	v_cvt_pk_bf16_f32 v34, v102, v103
	v_cvt_pk_bf16_f32 v35, v104, v105
	s_waitcnt lgkmcnt(14)
	s_nop 0
	v_mfma_f32_16x16x32_bf16 v[8:11], v[50:53], v[32:35], v[12:15]
	v_cvt_pk_bf16_f32 v50, v72, v73
	v_cvt_pk_bf16_f32 v51, v74, v75
	v_cvt_pk_bf16_f32 v52, v122, v123
	v_mfma_f32_16x16x32_bf16 v[12:15], v[130:133], v[32:35], v[28:31]
	v_cvt_pk_bf16_f32 v53, v124, v125
	s_waitcnt lgkmcnt(8)
	v_mfma_f32_16x16x32_bf16 v[20:23], v[142:145], v[32:35], v[20:23]
	v_mfma_f32_16x16x32_bf16 v[0:3], v[146:149], v[32:35], v[0:3]
	v_mfma_f32_16x16x32_bf16 v[16:19], v[134:137], v[50:53], v[8:11]
	v_mfma_f32_16x16x32_bf16 v[8:11], v[138:141], v[50:53], v[12:15]
	v_mfma_f32_16x16x32_bf16 v[20:23], v[150:153], v[50:53], v[20:23]
	v_mfma_f32_16x16x32_bf16 v[0:3], v[190:193], v[50:53], v[0:3]
	ds_read_b128 v[72:75], v99
	ds_read_b128 v[102:105], v99 offset:2048
	ds_read_b128 v[122:125], v100
	ds_read_b128 v[130:133], v100 offset:2048
	ds_read_b128 v[134:137], v99 offset:4096
	ds_read_b128 v[138:141], v99 offset:6144
	ds_read_b128 v[142:145], v100 offset:4096
	ds_read_b128 v[146:149], v100 offset:6144
	s_waitcnt lgkmcnt(8)
	v_mfma_f32_16x16x32_bf16 v[12:15], v[154:157], v[32:35], v[24:27]
	v_mfma_f32_16x16x32_bf16 v[28:31], v[170:173], v[32:35], v[40:43]
	v_mfma_f32_16x16x32_bf16 v[40:43], v[178:181], v[32:35], v[126:129]
	v_mfma_f32_16x16x32_bf16 v[4:7], v[186:189], v[32:35], v[4:7]
	v_mfma_f32_16x16x32_bf16 v[24:27], v[166:169], v[50:53], v[12:15]
	v_mfma_f32_16x16x32_bf16 v[12:15], v[174:177], v[50:53], v[28:31]
	v_mfma_f32_16x16x32_bf16 v[28:31], v[182:185], v[50:53], v[40:43]
	v_mfma_f32_16x16x32_bf16 v[4:7], v[194:197], v[50:53], v[4:7]
	s_waitcnt lgkmcnt(7)
	v_mfma_f32_16x16x32_bf16 v[40:43], v[72:75], v[32:35], v[110:113]
	s_waitcnt vmcnt(16)
	v_mov_b64_e32 v[76:77], v[238:239]
	v_mov_b64_e32 v[68:69], v[244:245]
	v_mov_b64_e32 v[38:39], v[60:61]
	s_waitcnt lgkmcnt(5)
	v_mfma_f32_16x16x32_bf16 v[40:43], v[122:125], v[50:53], v[40:43]
	s_mov_b32 s11, s8
	v_mov_b32_e32 v78, v79
	v_mov_b32_e32 v70, v205
	v_mfma_f32_16x16x32_bf16 v[72:75], v[102:105], v[32:35], v[114:117]
	s_waitcnt lgkmcnt(3)
	v_mfma_f32_16x16x32_bf16 v[102:105], v[134:137], v[32:35], v[118:121]
	s_nop 1
	v_cvt_pk_bf16_f32 v40, v40, s0
	v_cvt_pk_bf16_f32 v49, v41, s0
	s_waitcnt lgkmcnt(0)
	v_mfma_f32_16x16x32_bf16 v[32:35], v[138:141], v[32:35], v[106:109]
	v_mfma_f32_16x16x32_bf16 v[72:75], v[130:133], v[50:53], v[72:75]
	v_mfma_f32_16x16x32_bf16 v[102:105], v[142:145], v[50:53], v[102:105]
	v_mfma_f32_16x16x32_bf16 v[32:35], v[146:149], v[50:53], v[32:35]
	global_store_short v222, v40, s[18:19]
	v_cvt_pk_bf16_f32 v42, v42, s0
	global_store_short v223, v49, s[18:19]
	global_store_short v224, v42, s[18:19]
	v_cvt_pk_bf16_f32 v42, v43, s0
	global_store_short v225, v42, s[18:19]
	v_cvt_pk_bf16_f32 v42, v72, s0
	global_store_short v226, v42, s[18:19]
	v_cvt_pk_bf16_f32 v42, v73, s0
	v_mov_b64_e32 v[72:73], v[240:241]
	global_store_short v227, v42, s[18:19]
	v_cvt_pk_bf16_f32 v42, v74, s0
	global_store_short v228, v42, s[18:19]
	v_cvt_pk_bf16_f32 v42, v75, s0
	v_mov_b64_e32 v[74:75], v[242:243]
	global_store_short v229, v42, s[18:19]
	v_cvt_pk_bf16_f32 v42, v102, s0
	v_mov_b64_e32 v[36:37], v[66:67]
	global_store_short v230, v42, s[18:19]
	v_cvt_pk_bf16_f32 v42, v103, s0
	global_store_short v231, v42, s[18:19]
	v_cvt_pk_bf16_f32 v42, v104, s0
	global_store_short v232, v42, s[18:19]
	v_cvt_pk_bf16_f32 v42, v105, s0
	v_cvt_pk_bf16_f32 v32, v32, s0
	global_store_short v233, v42, s[18:19]
	global_store_short v234, v32, s[18:19]
	v_cvt_pk_bf16_f32 v40, v33, s0
	v_cvt_pk_bf16_f32 v34, v34, s0
	global_store_short v235, v40, s[18:19]
	global_store_short v236, v34, s[18:19]
	v_cvt_pk_bf16_f32 v34, v35, s0
	global_store_short v237, v34, s[18:19]
	v_mov_b64_e32 v[34:35], v[62:63]
	v_mov_b64_e32 v[32:33], v[64:65]
	s_barrier
	s_cbranch_scc0 .LBB0_1852

	.amdhsa_kernel _Z14fwd_megakernel6Params
		.amdhsa_group_segment_fixed_size 0
		.amdhsa_private_segment_fixed_size 0
		.amdhsa_kernarg_size 608
		.amdhsa_user_sgpr_count 2
		.amdhsa_user_sgpr_dispatch_ptr 0
		.amdhsa_user_sgpr_queue_ptr 0
		.amdhsa_user_sgpr_kernarg_segment_ptr 1
		.amdhsa_user_sgpr_dispatch_id 0
		.amdhsa_user_sgpr_kernarg_preload_length 0
		.amdhsa_user_sgpr_kernarg_preload_offset 0
		.amdhsa_user_sgpr_private_segment_size 0
		.amdhsa_uses_dynamic_stack 0
		.amdhsa_enable_private_segment 0
		.amdhsa_system_sgpr_workgroup_id_x 1
		.amdhsa_system_sgpr_workgroup_id_y 0
		.amdhsa_system_sgpr_workgroup_id_z 0
		.amdhsa_system_sgpr_workgroup_info 0
		.amdhsa_system_vgpr_workitem_id 2
		.amdhsa_next_free_vgpr 251
		.amdhsa_next_free_sgpr 100
		.amdhsa_accum_offset 252
		.amdhsa_reserve_vcc 1
		.amdhsa_float_round_mode_32 0
		.amdhsa_float_round_mode_16_64 0
		.amdhsa_float_denorm_mode_32 3
		.amdhsa_float_denorm_mode_16_64 3
		.amdhsa_dx10_clamp 1
		.amdhsa_ieee_mode 1
		.amdhsa_fp16_overflow 0
		.amdhsa_tg_split 0
		.amdhsa_exception_fp_ieee_invalid_op 0
		.amdhsa_exception_fp_denorm_src 0
		.amdhsa_exception_fp_ieee_div_zero 0
		.amdhsa_exception_fp_ieee_overflow 0
		.amdhsa_exception_fp_ieee_underflow 0
		.amdhsa_exception_fp_ieee_inexact 0
		.amdhsa_exception_int_div_zero 0
	.end_amdhsa_kernel

amdhsa.kernels:
  - .agpr_count:     0
    .args:
      - .offset:         0
        .size:           352
        .value_kind:     by_value
      - .offset:         352
        .size:           4
        .value_kind:     hidden_block_count_x
      - .offset:         356
        .size:           4
        .value_kind:     hidden_block_count_y
      - .offset:         360
        .size:           4
        .value_kind:     hidden_block_count_z
      - .offset:         364
        .size:           2
        .value_kind:     hidden_group_size_x
      - .offset:         366
        .size:           2
        .value_kind:     hidden_group_size_y
      - .offset:         368
        .size:           2
        .value_kind:     hidden_group_size_z
      - .offset:         370
        .size:           2
        .value_kind:     hidden_remainder_x
      - .offset:         372
        .size:           2
        .value_kind:     hidden_remainder_y
      - .offset:         374
        .size:           2
        .value_kind:     hidden_remainder_z
      - .offset:         392
        .size:           8
        .value_kind:     hidden_global_offset_x
      - .offset:         400
        .size:           8
        .value_kind:     hidden_global_offset_y
      - .offset:         408
        .size:           8
        .value_kind:     hidden_global_offset_z
      - .offset:         416
        .size:           2
        .value_kind:     hidden_grid_dims
      - .offset:         440
        .size:           8
        .value_kind:     hidden_multigrid_sync_arg
      - .offset:         472
        .size:           4
        .value_kind:     hidden_dynamic_lds_size
    .group_segment_fixed_size: 0
    .kernarg_segment_align: 8
    .kernarg_segment_size: 608
    .language:       OpenCL C
    .language_version:
      - 2
      - 0
    .max_flat_workgroup_size: 512
    .name:           _Z14fwd_megakernel6Params
    .private_segment_fixed_size: 0
    .sgpr_count:     106
    .sgpr_spill_count: 150
    .symbol:         _Z14fwd_megakernel6Params.kd
    .uniform_work_group_size: 1
    .uses_dynamic_stack: false
    .vgpr_count:     251
    .vgpr_spill_count: 0
    .wavefront_size: 64
